# MLA attention tile loop hand-rewritten: 2 barriers per tile, wave-half stagger, 3-slot LDS ring, pipelined K-fragment LDS reads, in-place P conversion
# baseline (speedup 1.0000x reference)
.LBB0_428:
	ds_bpermute_b32 v1, v246, v225
	s_mov_b64 s[4:5], 0
	s_waitcnt lgkmcnt(0)
	v_add_f32_e32 v1, v225, v1
	v_div_scale_f32 v2, s[2:3], v1, v1, 1.0
	v_rcp_f32_e32 v3, v2
	s_nop 0
	v_fma_f32 v4, -v2, v3, 1.0
	v_fmac_f32_e32 v3, v4, v3
	v_div_scale_f32 v4, vcc, 1.0, v1, 1.0
	v_mul_f32_e32 v5, v4, v3
	v_fma_f32 v6, -v2, v5, v4
	v_fmac_f32_e32 v5, v6, v3
	v_fma_f32 v2, -v2, v5, v4
	v_div_fmas_f32 v2, v2, v3, v5
	v_div_fixup_f32 v2, v2, v1, 1.0
	v_lshlrev_b64 v[4:5], 12, v[222:223]
	v_pk_mul_f32 v[6:7], v[96:97], v[2:3] op_sel_hi:[1,0]
	v_pk_mul_f32 v[8:9], v[98:99], v[2:3] op_sel_hi:[1,0]
	v_lshl_add_u64 v[4:5], v[214:215], 0, v[4:5]
	v_cvt_pk_bf16_f32 v6, v6, v7
	v_cvt_pk_bf16_f32 v7, v8, v9
	global_store_dwordx2 v[4:5], v[6:7], off
	v_pk_mul_f32 v[6:7], v[100:101], v[2:3] op_sel_hi:[1,0]
	v_pk_mul_f32 v[8:9], v[102:103], v[2:3] op_sel_hi:[1,0]
	v_cvt_pk_bf16_f32 v6, v6, v7
	v_cvt_pk_bf16_f32 v7, v8, v9
	global_store_dwordx2 v[4:5], v[6:7], off offset:16
	v_pk_mul_f32 v[6:7], v[104:105], v[2:3] op_sel_hi:[1,0]
	v_pk_mul_f32 v[8:9], v[106:107], v[2:3] op_sel_hi:[1,0]
	v_cvt_pk_bf16_f32 v6, v6, v7
	v_cvt_pk_bf16_f32 v7, v8, v9
	global_store_dwordx2 v[4:5], v[6:7], off offset:32
	v_pk_mul_f32 v[6:7], v[108:109], v[2:3] op_sel_hi:[1,0]
	v_pk_mul_f32 v[8:9], v[110:111], v[2:3] op_sel_hi:[1,0]
	v_cvt_pk_bf16_f32 v6, v6, v7
	v_cvt_pk_bf16_f32 v7, v8, v9
	global_store_dwordx2 v[4:5], v[6:7], off offset:48
	v_pk_mul_f32 v[6:7], v[80:81], v[2:3] op_sel_hi:[1,0]
	v_pk_mul_f32 v[8:9], v[82:83], v[2:3] op_sel_hi:[1,0]
	v_cvt_pk_bf16_f32 v6, v6, v7
	v_cvt_pk_bf16_f32 v7, v8, v9
	global_store_dwordx2 v[4:5], v[6:7], off offset:64
	v_pk_mul_f32 v[6:7], v[84:85], v[2:3] op_sel_hi:[1,0]
	v_pk_mul_f32 v[8:9], v[86:87], v[2:3] op_sel_hi:[1,0]
	v_cvt_pk_bf16_f32 v6, v6, v7
	v_cvt_pk_bf16_f32 v7, v8, v9
	global_store_dwordx2 v[4:5], v[6:7], off offset:80
	v_pk_mul_f32 v[6:7], v[88:89], v[2:3] op_sel_hi:[1,0]
	v_pk_mul_f32 v[8:9], v[90:91], v[2:3] op_sel_hi:[1,0]
	v_cvt_pk_bf16_f32 v6, v6, v7
	v_cvt_pk_bf16_f32 v7, v8, v9
	global_store_dwordx2 v[4:5], v[6:7], off offset:96
	v_pk_mul_f32 v[6:7], v[92:93], v[2:3] op_sel_hi:[1,0]
	v_pk_mul_f32 v[8:9], v[94:95], v[2:3] op_sel_hi:[1,0]
	v_cvt_pk_bf16_f32 v6, v6, v7
	v_cvt_pk_bf16_f32 v7, v8, v9
	global_store_dwordx2 v[4:5], v[6:7], off offset:112
	v_pk_mul_f32 v[6:7], v[64:65], v[2:3] op_sel_hi:[1,0]
	v_pk_mul_f32 v[8:9], v[66:67], v[2:3] op_sel_hi:[1,0]
	v_cvt_pk_bf16_f32 v6, v6, v7
	v_cvt_pk_bf16_f32 v7, v8, v9
	global_store_dwordx2 v[4:5], v[6:7], off offset:128
	v_pk_mul_f32 v[6:7], v[68:69], v[2:3] op_sel_hi:[1,0]
	v_pk_mul_f32 v[8:9], v[70:71], v[2:3] op_sel_hi:[1,0]
	v_cvt_pk_bf16_f32 v6, v6, v7
	v_cvt_pk_bf16_f32 v7, v8, v9
	global_store_dwordx2 v[4:5], v[6:7], off offset:144
	v_pk_mul_f32 v[6:7], v[72:73], v[2:3] op_sel_hi:[1,0]
	v_pk_mul_f32 v[8:9], v[74:75], v[2:3] op_sel_hi:[1,0]
	v_cvt_pk_bf16_f32 v6, v6, v7
	v_cvt_pk_bf16_f32 v7, v8, v9
	global_store_dwordx2 v[4:5], v[6:7], off offset:160
	v_pk_mul_f32 v[6:7], v[76:77], v[2:3] op_sel_hi:[1,0]
	v_pk_mul_f32 v[8:9], v[78:79], v[2:3] op_sel_hi:[1,0]
	v_cvt_pk_bf16_f32 v6, v6, v7
	v_cvt_pk_bf16_f32 v7, v8, v9
	global_store_dwordx2 v[4:5], v[6:7], off offset:176
	v_pk_mul_f32 v[6:7], v[48:49], v[2:3] op_sel_hi:[1,0]
	v_pk_mul_f32 v[8:9], v[50:51], v[2:3] op_sel_hi:[1,0]
	v_cvt_pk_bf16_f32 v6, v6, v7
	v_cvt_pk_bf16_f32 v7, v8, v9
	global_store_dwordx2 v[4:5], v[6:7], off offset:192
	v_pk_mul_f32 v[6:7], v[52:53], v[2:3] op_sel_hi:[1,0]
	v_pk_mul_f32 v[8:9], v[54:55], v[2:3] op_sel_hi:[1,0]
	v_cvt_pk_bf16_f32 v6, v6, v7
	v_cvt_pk_bf16_f32 v7, v8, v9
	global_store_dwordx2 v[4:5], v[6:7], off offset:208
	v_pk_mul_f32 v[6:7], v[56:57], v[2:3] op_sel_hi:[1,0]
	v_pk_mul_f32 v[8:9], v[58:59], v[2:3] op_sel_hi:[1,0]
	v_cvt_pk_bf16_f32 v6, v6, v7
	v_cvt_pk_bf16_f32 v7, v8, v9
	global_store_dwordx2 v[4:5], v[6:7], off offset:224
	v_pk_mul_f32 v[6:7], v[60:61], v[2:3] op_sel_hi:[1,0]
	v_pk_mul_f32 v[2:3], v[62:63], v[2:3] op_sel_hi:[1,0]
	v_cvt_pk_bf16_f32 v6, v6, v7
	v_cvt_pk_bf16_f32 v7, v2, v3
	s_and_b64 vcc, exec, s[10:11]
	global_store_dwordx2 v[4:5], v[6:7], off offset:240
	s_cmpk_ge_i32 s13, 0x80
	s_cbranch_scc1 .Lmla_skip_xbar_a
	s_barrier
.Lmla_skip_xbar_a:
	s_barrier
	s_cbranch_vccnz .LBB0_425
.LBB0_429:
	s_xor_b64 s[10:11], s[4:5], -1
	s_and_b64 s[2:3], s[4:5], exec
	s_cselect_b32 s2, s15, s14
	s_lshl_b32 s2, s2, 8
	s_add_i32 s18, s2, s13
	v_or_b32_e32 v224, s18, v185
	v_ashrrev_i32_e32 v225, 31, v224
	v_lshl_add_u64 v[222:223], s[0:1], 0, v[224:225]
	s_movk_i32 s3, 0x1800
	v_mad_u64_u32 v[6:7], s[4:5], v222, s3, v[202:203]
	v_lshlrev_b64 v[14:15], 8, v[224:225]
	v_mad_i32_i24 v7, v223, s3, v7
	v_lshl_add_u64 v[14:15], v[174:175], 0, v[14:15]
	global_load_dwordx4 v[148:151], v[6:7], off
	global_load_dwordx4 v[144:147], v[6:7], off offset:32
	global_load_dwordx4 v[140:143], v[6:7], off offset:64
	global_load_dwordx4 v[132:135], v[6:7], off offset:96
	global_load_dwordx4 v[124:127], v[6:7], off offset:128
	global_load_dwordx4 v[120:123], v[6:7], off offset:160
	global_load_dwordx4 v[116:119], v[6:7], off offset:192
	global_load_dwordx4 v[112:115], v[6:7], off offset:224
	global_load_dwordx4 v[10:13], v[6:7], off offset:256
	global_load_dwordx4 v[2:5], v[6:7], off offset:288
	global_load_dwordx4 v[48:51], v[6:7], off offset:320
	s_nop 0
	global_load_dwordx4 v[6:9], v[6:7], off offset:352
	s_nop 0
	global_load_dwordx4 v[52:55], v[14:15], off offset:48
	global_load_dwordx4 v[56:59], v[14:15], off offset:32
	global_load_dwordx4 v[60:63], v[14:15], off offset:16
	global_load_dwordx4 v[64:67], v[14:15], off
	v_add_u32_e32 v1, v190, v242
	s_or_b32 s16, s18, 31
	s_or_b32 s3, s2, 0xc0
	s_mov_b32 s19, 0
	v_mov_b32_e32 v249, 0xf149f2ca
	v_mov_b32_e32 v225, 0
	v_mov_b64_e32 v[226:227], v[220:221]
	v_mov_b64_e32 v[228:229], v[218:219]
	s_mov_b64 s[4:5], 0x2000
	v_lshl_add_u64 v[228:229], v[228:229], 0, s[4:5]
	v_mov_b64_e32 v[230:231], v[216:217]
	s_mov_b32 s24, 0
	s_waitcnt vmcnt(0)
	v_and_b32_e32 v69, 0xffff0000, v10
	v_lshlrev_b32_e32 v68, 16, v10
	v_and_b32_e32 v71, 0xffff0000, v48
	v_lshlrev_b32_e32 v70, 16, v48
	v_mov_b32_e32 v73, v66
	v_mov_b32_e32 v66, v65
	v_mov_b32_e32 v72, v64
	v_pk_mul_f32 v[64:65], v[66:67], v[70:71]
	v_lshlrev_b32_e32 v10, 16, v49
	v_pk_fma_f32 v[64:65], v[72:73], v[68:69], v[64:65] neg_lo:[0,0,1] neg_hi:[0,0,1]
	v_mov_b32_e32 v48, v60
	v_cvt_pk_bf16_f32 v136, v64, v65
	v_pk_mul_f32 v[64:65], v[72:73], v[70:71]
	s_nop 0
	v_pk_fma_f32 v[64:65], v[66:67], v[68:69], v[64:65]
	s_nop 0
	v_cvt_pk_bf16_f32 v128, v64, v65
	v_and_b32_e32 v65, 0xffff0000, v11
	v_lshlrev_b32_e32 v64, 16, v11
	v_and_b32_e32 v11, 0xffff0000, v49
	v_mov_b32_e32 v49, v62
	v_mov_b32_e32 v62, v61
	v_pk_mul_f32 v[60:61], v[62:63], v[10:11]
	v_pk_mul_f32 v[10:11], v[48:49], v[10:11]
	v_pk_fma_f32 v[60:61], v[48:49], v[64:65], v[60:61] neg_lo:[0,0,1] neg_hi:[0,0,1]
	v_pk_fma_f32 v[10:11], v[62:63], v[64:65], v[10:11]
	v_cvt_pk_bf16_f32 v137, v60, v61
	v_and_b32_e32 v49, 0xffff0000, v50
	v_lshlrev_b32_e32 v48, 16, v50
	v_mov_b32_e32 v60, v56
	v_mov_b32_e32 v61, v58
	v_mov_b32_e32 v58, v57
	v_cvt_pk_bf16_f32 v129, v10, v11
	v_and_b32_e32 v11, 0xffff0000, v12
	v_lshlrev_b32_e32 v10, 16, v12
	v_pk_mul_f32 v[56:57], v[58:59], v[48:49]
	v_pk_mul_f32 v[48:49], v[60:61], v[48:49]
	v_pk_fma_f32 v[56:57], v[60:61], v[10:11], v[56:57] neg_lo:[0,0,1] neg_hi:[0,0,1]
	v_pk_fma_f32 v[10:11], v[58:59], v[10:11], v[48:49]
	v_lshlrev_b32_e32 v12, 16, v51
	v_cvt_pk_bf16_f32 v130, v10, v11
	v_and_b32_e32 v11, 0xffff0000, v13
	v_lshlrev_b32_e32 v10, 16, v13
	v_and_b32_e32 v13, 0xffff0000, v51
	v_mov_b32_e32 v48, v52
	v_mov_b32_e32 v49, v54
	v_mov_b32_e32 v54, v53
	v_pk_mul_f32 v[50:51], v[54:55], v[12:13]
	v_pk_mul_f32 v[12:13], v[48:49], v[12:13]
	v_pk_fma_f32 v[50:51], v[48:49], v[10:11], v[50:51] neg_lo:[0,0,1] neg_hi:[0,0,1]
	v_pk_fma_f32 v[10:11], v[54:55], v[10:11], v[12:13]
	v_cvt_pk_bf16_f32 v138, v56, v57
	v_cvt_pk_bf16_f32 v139, v50, v51
	v_cvt_pk_bf16_f32 v131, v10, v11
	global_load_dwordx4 v[10:13], v[14:15], off offset:176
	global_load_dwordx4 v[48:51], v[14:15], off offset:160
	global_load_dwordx4 v[52:55], v[14:15], off offset:144
	global_load_dwordx4 v[56:59], v[14:15], off offset:128
	v_and_b32_e32 v61, 0xffff0000, v6
	v_lshlrev_b32_e32 v60, 16, v6
	v_and_b32_e32 v15, 0xffff0000, v2
	v_lshlrev_b32_e32 v14, 16, v2
	v_lshlrev_b32_e32 v2, 16, v7
	s_waitcnt vmcnt(0)
	v_mov_b32_e32 v6, v52
	v_mov_b32_e32 v63, v58
	v_mov_b32_e32 v58, v57
	v_mov_b32_e32 v62, v56
	v_pk_mul_f32 v[56:57], v[58:59], v[60:61]
	s_nop 0
	v_pk_fma_f32 v[56:57], v[62:63], v[14:15], v[56:57] neg_lo:[0,0,1] neg_hi:[0,0,1]
	s_nop 0
	v_cvt_pk_bf16_f32 v156, v56, v57
	v_pk_mul_f32 v[56:57], v[62:63], v[60:61]
	s_nop 0
	v_pk_fma_f32 v[14:15], v[58:59], v[14:15], v[56:57]
	s_nop 0
	v_cvt_pk_bf16_f32 v152, v14, v15
	v_and_b32_e32 v15, 0xffff0000, v3
	v_lshlrev_b32_e32 v14, 16, v3
	v_and_b32_e32 v3, 0xffff0000, v7
	v_mov_b32_e32 v7, v54
	v_mov_b32_e32 v54, v53
	v_pk_mul_f32 v[52:53], v[54:55], v[2:3]
	v_pk_mul_f32 v[2:3], v[6:7], v[2:3]
	v_pk_fma_f32 v[52:53], v[6:7], v[14:15], v[52:53] neg_lo:[0,0,1] neg_hi:[0,0,1]
	v_pk_fma_f32 v[2:3], v[54:55], v[14:15], v[2:3]
	v_and_b32_e32 v7, 0xffff0000, v8
	v_lshlrev_b32_e32 v6, 16, v8
	v_mov_b32_e32 v14, v48
	v_mov_b32_e32 v15, v50
	v_mov_b32_e32 v50, v49
	v_cvt_pk_bf16_f32 v153, v2, v3
	v_and_b32_e32 v3, 0xffff0000, v4
	v_lshlrev_b32_e32 v2, 16, v4
	v_pk_mul_f32 v[48:49], v[50:51], v[6:7]
	v_pk_mul_f32 v[6:7], v[14:15], v[6:7]
	v_pk_fma_f32 v[48:49], v[14:15], v[2:3], v[48:49] neg_lo:[0,0,1] neg_hi:[0,0,1]
	v_pk_fma_f32 v[2:3], v[50:51], v[2:3], v[6:7]
	v_lshlrev_b32_e32 v4, 16, v9
	v_cvt_pk_bf16_f32 v154, v2, v3
	v_and_b32_e32 v3, 0xffff0000, v5
	v_lshlrev_b32_e32 v2, 16, v5
	v_and_b32_e32 v5, 0xffff0000, v9
	v_mov_b32_e32 v6, v10
	v_mov_b32_e32 v7, v12
	v_mov_b32_e32 v12, v11
	v_pk_mul_f32 v[8:9], v[12:13], v[4:5]
	v_pk_mul_f32 v[4:5], v[6:7], v[4:5]
	v_pk_fma_f32 v[8:9], v[6:7], v[2:3], v[8:9] neg_lo:[0,0,1] neg_hi:[0,0,1]
	v_pk_fma_f32 v[2:3], v[12:13], v[2:3], v[4:5]
	v_cvt_pk_bf16_f32 v157, v52, v53
	v_cvt_pk_bf16_f32 v158, v48, v49
	v_cvt_pk_bf16_f32 v159, v8, v9
	v_cvt_pk_bf16_f32 v155, v2, v3
	global_load_dwordx4 v[2:5], v[204:205], off
	global_load_dwordx4 v[6:9], v[206:207], off
	global_load_dwordx4 v[52:55], v[208:209], off
	global_load_dwordx4 v[48:51], v[210:211], off
	global_load_dwordx4 v[10:13], v[212:213], off
	s_waitcnt vmcnt(0)
	ds_write_b128 v247, v[2:5]
	ds_write_b128 v247, v[6:9] offset:12800
	ds_write_b128 v1, v[52:55] offset:256
	v_add_u32_e32 v1, 0x6400, v248
	ds_write2_b64 v1, v[48:49], v[50:51] offset1:1
	v_add_u32_e32 v1, 0x8600, v248
	v_mov_b32_e32 v14, v0
	v_mov_b32_e32 v15, v0
	ds_write2_b64 v1, v[10:11], v[12:13] offset1:1
	s_mov_b64 s[4:5], 0x40000
	v_lshl_add_u64 v[2:3], v[204:205], 0, s[4:5]
	v_lshl_add_u64 v[4:5], v[206:207], 0, s[4:5]
	s_mov_b64 s[4:5], 0x2000
	v_lshl_add_u64 v[6:7], v[208:209], 0, s[4:5]
	global_load_dwordx4 v[56:59], v[2:3], off
	global_load_dwordx4 v[60:63], v[4:5], off
	global_load_dwordx4 v[64:67], v[6:7], off
	global_load_dwordx4 v[68:71], v[210:211], off offset:128
	global_load_dwordx4 v[72:75], v[212:213], off offset:128
	s_waitcnt vmcnt(0)
	ds_write_b128 v247, v[56:59] offset:43008
	ds_write_b128 v247, v[60:63] offset:55808
	v_add_u32_e32 v1, v190, v242
	ds_write_b128 v1, v[64:67] offset:43264
	v_add_u32_e32 v1, 0x10c00, v248
	ds_write2_b64 v1, v[68:69], v[70:71] offset1:1
	v_add_u32_e32 v1, 0x12e00, v248
	ds_write2_b64 v1, v[72:73], v[74:75] offset1:1
	v_mov_b32_e32 v1, v0
	v_mov_b32_e32 v2, v0
	v_mov_b32_e32 v3, v0
	v_mov_b32_e32 v4, v0
	v_mov_b32_e32 v5, v0
	v_mov_b32_e32 v6, v0
	v_mov_b32_e32 v7, v0
	v_mov_b32_e32 v8, v0
	v_mov_b32_e32 v9, v0
	v_mov_b32_e32 v10, v0
	v_mov_b32_e32 v11, v0
	v_mov_b32_e32 v12, v0
	v_mov_b32_e32 v13, v0
	v_mov_b64_e32 v[62:63], v[14:15]
	v_mov_b64_e32 v[78:79], v[14:15]
	v_mov_b64_e32 v[94:95], v[14:15]
	v_mov_b64_e32 v[110:111], v[14:15]
	v_mov_b64_e32 v[60:61], v[12:13]
	v_mov_b64_e32 v[58:59], v[10:11]
	v_mov_b64_e32 v[56:57], v[8:9]
	v_mov_b64_e32 v[54:55], v[6:7]
	v_mov_b64_e32 v[52:53], v[4:5]
	v_mov_b64_e32 v[50:51], v[2:3]
	v_mov_b64_e32 v[48:49], v[0:1]
	v_mov_b64_e32 v[76:77], v[12:13]
	v_mov_b64_e32 v[74:75], v[10:11]
	v_mov_b64_e32 v[72:73], v[8:9]
	v_mov_b64_e32 v[70:71], v[6:7]
	v_mov_b64_e32 v[68:69], v[4:5]
	v_mov_b64_e32 v[66:67], v[2:3]
	v_mov_b64_e32 v[64:65], v[0:1]
	v_mov_b64_e32 v[92:93], v[12:13]
	v_mov_b64_e32 v[90:91], v[10:11]
	v_mov_b64_e32 v[88:89], v[8:9]
	v_mov_b64_e32 v[86:87], v[6:7]
	v_mov_b64_e32 v[84:85], v[4:5]
	v_mov_b64_e32 v[82:83], v[2:3]
	v_mov_b64_e32 v[80:81], v[0:1]
	v_mov_b64_e32 v[108:109], v[12:13]
	v_mov_b64_e32 v[106:107], v[10:11]
	v_mov_b64_e32 v[104:105], v[8:9]
	v_mov_b64_e32 v[102:103], v[6:7]
	v_mov_b64_e32 v[100:101], v[4:5]
	v_mov_b64_e32 v[98:99], v[2:3]
	v_mov_b64_e32 v[96:97], v[0:1]
	s_cmpk_lt_i32 s13, 0x80
	s_cbranch_scc1 .Lmla_skip_xbar_b
	s_waitcnt lgkmcnt(0)
	s_barrier

.LBB0_432:
	s_waitcnt lgkmcnt(0)
	s_barrier
	s_add_i32 s25, s24, 16
	s_cmp_gt_i32 s19, s16
	s_cbranch_scc1 .Lmla_h1_done
	v_add3_u32 v1, s25, v244, v170
	ds_read_b128 v[2:5], v1
	ds_read_b128 v[6:9], v1 offset:12800
	ds_read_b128 v[10:13], v1 offset:32
	ds_read_b128 v[160:163], v1 offset:12832
	ds_read_b128 v[164:167], v1 offset:64
	ds_read_b128 v[186:189], v1 offset:12864
	s_waitcnt lgkmcnt(5)
	v_mfma_f32_32x32x16_bf16 v[16:31], v[2:5], v[148:151], 0
	ds_read_b128 v[2:5], v1 offset:96
	s_waitcnt lgkmcnt(5)
	v_mfma_f32_32x32x16_bf16 v[32:47], v[6:9], v[148:151], 0
	ds_read_b128 v[6:9], v1 offset:12896
	s_waitcnt lgkmcnt(5)
	v_mfma_f32_32x32x16_bf16 v[16:31], v[10:13], v[144:147], v[16:31]
	ds_read_b128 v[10:13], v1 offset:128
	s_waitcnt lgkmcnt(5)
	v_mfma_f32_32x32x16_bf16 v[32:47], v[160:163], v[144:147], v[32:47]
	ds_read_b128 v[160:163], v1 offset:12928
	s_waitcnt lgkmcnt(5)
	v_mfma_f32_32x32x16_bf16 v[16:31], v[164:167], v[140:143], v[16:31]
	ds_read_b128 v[164:167], v1 offset:160
	s_waitcnt lgkmcnt(5)
	v_mfma_f32_32x32x16_bf16 v[32:47], v[186:189], v[140:143], v[32:47]
	ds_read_b128 v[186:189], v1 offset:12960
	s_waitcnt lgkmcnt(5)
	v_mfma_f32_32x32x16_bf16 v[16:31], v[2:5], v[132:135], v[16:31]
	ds_read_b128 v[2:5], v1 offset:192
	s_waitcnt lgkmcnt(5)
	v_mfma_f32_32x32x16_bf16 v[32:47], v[6:9], v[132:135], v[32:47]
	ds_read_b128 v[6:9], v1 offset:12992
	s_waitcnt lgkmcnt(5)
	v_mfma_f32_32x32x16_bf16 v[16:31], v[10:13], v[124:127], v[16:31]
	ds_read_b128 v[10:13], v1 offset:224
	s_waitcnt lgkmcnt(5)
	v_mfma_f32_32x32x16_bf16 v[32:47], v[160:163], v[124:127], v[32:47]
	ds_read_b128 v[160:163], v1 offset:13024
	s_waitcnt lgkmcnt(5)
	v_mfma_f32_32x32x16_bf16 v[16:31], v[164:167], v[120:123], v[16:31]
	ds_read_b128 v[164:167], v1 offset:256
	s_waitcnt lgkmcnt(5)
	v_mfma_f32_32x32x16_bf16 v[32:47], v[186:189], v[120:123], v[32:47]
	ds_read_b128 v[186:189], v1 offset:13056
	s_waitcnt lgkmcnt(5)
	v_mfma_f32_32x32x16_bf16 v[16:31], v[2:5], v[116:119], v[16:31]
	ds_read_b128 v[2:5], v1 offset:288
	s_waitcnt lgkmcnt(5)
	v_mfma_f32_32x32x16_bf16 v[32:47], v[6:9], v[116:119], v[32:47]
	ds_read_b128 v[6:9], v1 offset:13088
	s_waitcnt lgkmcnt(5)
	v_mfma_f32_32x32x16_bf16 v[16:31], v[10:13], v[112:115], v[16:31]
	ds_read_b128 v[10:13], v1 offset:320
	s_waitcnt lgkmcnt(5)
	v_mfma_f32_32x32x16_bf16 v[32:47], v[160:163], v[112:115], v[32:47]
	ds_read_b128 v[160:163], v1 offset:13120
	s_waitcnt lgkmcnt(5)
	v_mfma_f32_32x32x16_bf16 v[16:31], v[164:167], v[136:139], v[16:31]
	ds_read_b128 v[164:167], v1 offset:352
	s_waitcnt lgkmcnt(5)
	v_mfma_f32_32x32x16_bf16 v[32:47], v[186:189], v[136:139], v[32:47]
	ds_read_b128 v[186:189], v1 offset:13152
	s_waitcnt lgkmcnt(5)
	v_mfma_f32_32x32x16_bf16 v[16:31], v[2:5], v[156:159], v[16:31]
	s_waitcnt lgkmcnt(4)
	v_mfma_f32_32x32x16_bf16 v[32:47], v[6:9], v[156:159], v[32:47]
	s_waitcnt lgkmcnt(3)
	v_mfma_f32_32x32x16_bf16 v[16:31], v[10:13], v[128:131], v[16:31]
	s_waitcnt lgkmcnt(2)
	v_mfma_f32_32x32x16_bf16 v[32:47], v[160:163], v[128:131], v[32:47]
	s_waitcnt lgkmcnt(1)
	v_mfma_f32_32x32x16_bf16 v[16:31], v[164:167], v[152:155], v[16:31]
	s_waitcnt lgkmcnt(0)
	v_mfma_f32_32x32x16_bf16 v[32:47], v[186:189], v[152:155], v[32:47]
.Lmla_h1_done:
	s_barrier
	v_lshl_add_u64 v[2:3], s[90:91], 0, v[226:227]
	s_mov_b32 s2, 0x1e180000
	v_add_co_u32_e32 v4, vcc, s2, v2
	s_mov_b32 s2, 0x1e1a0000
	s_nop 0
	v_addc_co_u32_e32 v5, vcc, 0, v3, vcc
	v_add_co_u32_e32 v6, vcc, s2, v2
	v_lshl_add_u64 v[14:15], s[90:91], 0, v[230:231]
	s_nop 0
	v_addc_co_u32_e32 v7, vcc, 0, v3, vcc
	s_mov_b32 s2, 0x20100000
	v_add_co_u32_e32 v160, vcc, s2, v14
	v_lshl_add_u64 v[10:11], s[90:91], 0, v[228:229]
	s_nop 0
	v_addc_co_u32_e32 v161, vcc, 0, v15, vcc
	v_add_co_u32_e32 v14, vcc, 0x20200000, v14
	s_nop 1
	v_addc_co_u32_e32 v15, vcc, 0, v15, vcc
	global_load_dwordx4 v[2:5], v[4:5], off
	s_nop 0
	global_load_dwordx4 v[6:9], v[6:7], off
	s_nop 0
	global_load_dwordx4 v[10:13], v[10:11], off
	s_nop 0
	global_load_dwordx4 v[160:163], v[160:161], off offset:256
	global_load_dwordx4 v[164:167], v[14:15], off offset:256
	s_cmp_gt_i32 s19, s16
	s_cbranch_scc1 .Lmla_h2_done
	s_add_i32 s4, s19, 63
	s_cmp_lt_i32 s4, s18
	s_cbranch_scc1 .Lmla_nomask
	v_add_u32_e32 v14, s19, v245
	v_sub_u32_e32 v14, v224, v14
	v_cmp_le_i32_e32 vcc, 0, v14
	s_nop 1
	v_cndmask_b32_e32 v16, v237, v16, vcc
	v_cmp_le_i32_e32 vcc, 1, v14
	s_nop 1
	v_cndmask_b32_e32 v17, v237, v17, vcc
	v_cmp_le_i32_e32 vcc, 2, v14
	s_nop 1
	v_cndmask_b32_e32 v18, v237, v18, vcc
	v_cmp_le_i32_e32 vcc, 3, v14
	s_nop 1
	v_cndmask_b32_e32 v19, v237, v19, vcc
	v_cmp_le_i32_e32 vcc, 8, v14
	s_nop 1
	v_cndmask_b32_e32 v20, v237, v20, vcc
	v_cmp_le_i32_e32 vcc, 9, v14
	s_nop 1
	v_cndmask_b32_e32 v21, v237, v21, vcc
	v_cmp_le_i32_e32 vcc, 10, v14
	s_nop 1
	v_cndmask_b32_e32 v22, v237, v22, vcc
	v_cmp_le_i32_e32 vcc, 11, v14
	s_nop 1
	v_cndmask_b32_e32 v23, v237, v23, vcc
	v_cmp_le_i32_e32 vcc, 16, v14
	s_nop 1
	v_cndmask_b32_e32 v24, v237, v24, vcc
	v_cmp_le_i32_e32 vcc, 17, v14
	s_nop 1
	v_cndmask_b32_e32 v25, v237, v25, vcc
	v_cmp_le_i32_e32 vcc, 18, v14
	s_nop 1
	v_cndmask_b32_e32 v26, v237, v26, vcc
	v_cmp_le_i32_e32 vcc, 19, v14
	s_nop 1
	v_cndmask_b32_e32 v27, v237, v27, vcc
	v_cmp_le_i32_e32 vcc, 24, v14
	s_nop 1
	v_cndmask_b32_e32 v28, v237, v28, vcc
	v_cmp_le_i32_e32 vcc, 25, v14
	s_nop 1
	v_cndmask_b32_e32 v29, v237, v29, vcc
	v_cmp_le_i32_e32 vcc, 26, v14
	s_nop 1
	v_cndmask_b32_e32 v30, v237, v30, vcc
	v_cmp_le_i32_e32 vcc, 27, v14
	s_nop 1
	v_cndmask_b32_e32 v31, v237, v31, vcc
	v_cmp_le_i32_e32 vcc, 32, v14
	s_nop 1
	v_cndmask_b32_e32 v32, v237, v32, vcc
	v_cmp_le_i32_e32 vcc, 33, v14
	s_nop 1
	v_cndmask_b32_e32 v33, v237, v33, vcc
	v_cmp_le_i32_e32 vcc, 34, v14
	s_nop 1
	v_cndmask_b32_e32 v34, v237, v34, vcc
	v_cmp_le_i32_e32 vcc, 35, v14
	s_nop 1
	v_cndmask_b32_e32 v35, v237, v35, vcc
	v_cmp_le_i32_e32 vcc, 40, v14
	s_nop 1
	v_cndmask_b32_e32 v36, v237, v36, vcc
	v_cmp_le_i32_e32 vcc, 41, v14
	s_nop 1
	v_cndmask_b32_e32 v37, v237, v37, vcc
	v_cmp_le_i32_e32 vcc, 42, v14
	s_nop 1
	v_cndmask_b32_e32 v38, v237, v38, vcc
	v_cmp_le_i32_e32 vcc, 43, v14
	s_nop 1
	v_cndmask_b32_e32 v39, v237, v39, vcc
	v_cmp_le_i32_e32 vcc, 48, v14
	s_nop 1
	v_cndmask_b32_e32 v40, v237, v40, vcc
	v_cmp_le_i32_e32 vcc, 49, v14
	s_nop 1
	v_cndmask_b32_e32 v41, v237, v41, vcc
	v_cmp_le_i32_e32 vcc, 50, v14
	s_nop 1
	v_cndmask_b32_e32 v42, v237, v42, vcc
	v_cmp_le_i32_e32 vcc, 51, v14
	s_nop 1
	v_cndmask_b32_e32 v43, v237, v43, vcc
	v_cmp_le_i32_e32 vcc, 56, v14
	s_nop 1
	v_cndmask_b32_e32 v44, v237, v44, vcc
	v_cmp_le_i32_e32 vcc, 57, v14
	s_nop 1
	v_cndmask_b32_e32 v45, v237, v45, vcc
	v_cmp_le_i32_e32 vcc, 58, v14
	s_nop 1
	v_cndmask_b32_e32 v46, v237, v46, vcc
	v_cmp_le_i32_e32 vcc, 59, v14
	s_nop 1
	v_cndmask_b32_e32 v47, v237, v47, vcc
.Lmla_nomask:
	v_max3_f32 v1, v16, v17, s49
	v_max3_f32 v1, v1, v18, v19
	v_max3_f32 v1, v1, v20, v21
	v_max3_f32 v1, v1, v22, v23
	v_max3_f32 v1, v1, v24, v25
	v_max3_f32 v1, v1, v26, v27
	v_max3_f32 v1, v1, v28, v29
	v_max3_f32 v1, v1, v30, v31
	v_max3_f32 v1, v1, v32, v33
	v_max3_f32 v1, v1, v34, v35
	v_max3_f32 v1, v1, v36, v37
	v_max3_f32 v1, v1, v38, v39
	v_max3_f32 v1, v1, v40, v41
	v_max3_f32 v1, v1, v42, v43
	v_max3_f32 v1, v1, v44, v45
	v_max3_f32 v1, v1, v46, v47
	ds_bpermute_b32 v15, v246, v1
	s_waitcnt lgkmcnt(0)
	v_max_f32_e32 v1, v1, v15
	v_mul_f32_e32 v1, 0x3dd53b94, v1
	v_max_f32_e32 v1, v249, v1
	v_sub_f32_e32 v14, v249, v1
	v_exp_f32_e32 v14, v14
	v_mov_b32_e32 v249, v1
	v_fma_f32 v16, v16, s50, -v1
	v_exp_f32_e32 v16, v16
	v_fma_f32 v17, v17, s50, -v1
	v_exp_f32_e32 v17, v17
	v_fma_f32 v18, v18, s50, -v1
	v_exp_f32_e32 v18, v18
	v_fma_f32 v19, v19, s50, -v1
	v_exp_f32_e32 v19, v19
	v_fma_f32 v20, v20, s50, -v1
	v_exp_f32_e32 v20, v20
	v_fma_f32 v21, v21, s50, -v1
	v_exp_f32_e32 v21, v21
	v_fma_f32 v22, v22, s50, -v1
	v_exp_f32_e32 v22, v22
	v_fma_f32 v23, v23, s50, -v1
	v_exp_f32_e32 v23, v23
	v_fma_f32 v24, v24, s50, -v1
	v_exp_f32_e32 v24, v24
	v_fma_f32 v25, v25, s50, -v1
	v_exp_f32_e32 v25, v25
	v_fma_f32 v26, v26, s50, -v1
	v_exp_f32_e32 v26, v26
	v_fma_f32 v27, v27, s50, -v1
	v_exp_f32_e32 v27, v27
	v_fma_f32 v28, v28, s50, -v1
	v_exp_f32_e32 v28, v28
	v_fma_f32 v29, v29, s50, -v1
	v_exp_f32_e32 v29, v29
	v_fma_f32 v30, v30, s50, -v1
	v_exp_f32_e32 v30, v30
	v_fma_f32 v31, v31, s50, -v1
	v_exp_f32_e32 v31, v31
	v_fma_f32 v32, v32, s50, -v1
	v_exp_f32_e32 v32, v32
	v_fma_f32 v33, v33, s50, -v1
	v_exp_f32_e32 v33, v33
	v_fma_f32 v34, v34, s50, -v1
	v_exp_f32_e32 v34, v34
	v_fma_f32 v35, v35, s50, -v1
	v_exp_f32_e32 v35, v35
	v_fma_f32 v36, v36, s50, -v1
	v_exp_f32_e32 v36, v36
	v_fma_f32 v37, v37, s50, -v1
	v_exp_f32_e32 v37, v37
	v_fma_f32 v38, v38, s50, -v1
	v_exp_f32_e32 v38, v38
	v_fma_f32 v39, v39, s50, -v1
	v_exp_f32_e32 v39, v39
	v_fma_f32 v40, v40, s50, -v1
	v_exp_f32_e32 v40, v40
	v_fma_f32 v41, v41, s50, -v1
	v_exp_f32_e32 v41, v41
	v_fma_f32 v42, v42, s50, -v1
	v_exp_f32_e32 v42, v42
	v_fma_f32 v43, v43, s50, -v1
	v_exp_f32_e32 v43, v43
	v_fma_f32 v44, v44, s50, -v1
	v_exp_f32_e32 v44, v44
	v_fma_f32 v45, v45, s50, -v1
	v_exp_f32_e32 v45, v45
	v_fma_f32 v46, v46, s50, -v1
	v_exp_f32_e32 v46, v46
	v_fma_f32 v47, v47, s50, -v1
	v_exp_f32_e32 v47, v47
	v_pk_mul_f32 v[96:97], v[96:97], v[14:15] op_sel_hi:[1,0]
	v_pk_mul_f32 v[98:99], v[98:99], v[14:15] op_sel_hi:[1,0]
	v_pk_mul_f32 v[100:101], v[100:101], v[14:15] op_sel_hi:[1,0]
	v_pk_mul_f32 v[102:103], v[102:103], v[14:15] op_sel_hi:[1,0]
	v_pk_mul_f32 v[104:105], v[104:105], v[14:15] op_sel_hi:[1,0]
	v_pk_mul_f32 v[106:107], v[106:107], v[14:15] op_sel_hi:[1,0]
	v_pk_mul_f32 v[108:109], v[108:109], v[14:15] op_sel_hi:[1,0]
	v_pk_mul_f32 v[110:111], v[110:111], v[14:15] op_sel_hi:[1,0]
	v_add_f32_e32 v1, v16, v17
	v_add_f32_e32 v15, v24, v25
	v_add_f32_e32 v238, v32, v33
	v_add_f32_e32 v186, v40, v41
	v_add_f32_e32 v1, v18, v1
	v_add_f32_e32 v15, v26, v15
	v_add_f32_e32 v238, v34, v238
	v_add_f32_e32 v186, v42, v186
	v_add_f32_e32 v1, v19, v1
	v_add_f32_e32 v15, v27, v15
	v_add_f32_e32 v238, v35, v238
	v_add_f32_e32 v186, v43, v186
	v_add_f32_e32 v1, v20, v1
	v_add_f32_e32 v15, v28, v15
	v_add_f32_e32 v238, v36, v238
	v_add_f32_e32 v186, v44, v186
	v_add_f32_e32 v1, v21, v1
	v_add_f32_e32 v15, v29, v15
	v_add_f32_e32 v238, v37, v238
	v_add_f32_e32 v186, v45, v186
	v_add_f32_e32 v1, v22, v1
	v_add_f32_e32 v15, v30, v15
	v_add_f32_e32 v238, v38, v238
	v_add_f32_e32 v186, v46, v186
	v_add_f32_e32 v1, v23, v1
	v_add_f32_e32 v15, v31, v15
	v_add_f32_e32 v238, v39, v238
	v_add_f32_e32 v186, v47, v186
	v_add_f32_e32 v1, v1, v15
	v_add_f32_e32 v238, v238, v186
	v_add_f32_e32 v1, v1, v238
	v_fmac_f32_e32 v1, v225, v14
	v_mov_b32_e32 v225, v1
	v_add3_u32 v186, s25, v168, v169
	v_add_u32_e32 v187, 0x7000, v186
	v_add_u32_e32 v188, 0x8000, v186
	v_add_u32_e32 v189, 0x9000, v186
	v_add_u32_e32 v186, 0x6000, v186
	v_cvt_pk_bf16_f32 v16, v16, v17
	v_cvt_pk_bf16_f32 v17, v18, v19
	v_cvt_pk_bf16_f32 v18, v20, v21
	v_cvt_pk_bf16_f32 v19, v22, v23
	v_cvt_pk_bf16_f32 v20, v24, v25
	v_cvt_pk_bf16_f32 v21, v26, v27
	v_cvt_pk_bf16_f32 v22, v28, v29
	v_cvt_pk_bf16_f32 v23, v30, v31
	v_cvt_pk_bf16_f32 v24, v32, v33
	v_cvt_pk_bf16_f32 v25, v34, v35
	v_cvt_pk_bf16_f32 v26, v36, v37
	v_cvt_pk_bf16_f32 v27, v38, v39
	v_cvt_pk_bf16_f32 v28, v40, v41
	v_cvt_pk_bf16_f32 v29, v42, v43
	v_cvt_pk_bf16_f32 v30, v44, v45
	v_cvt_pk_bf16_f32 v31, v46, v47
	ds_read2_b64 v[32:35], v186 offset0:128 offset1:130
	ds_read2_b64 v[36:39], v186 offset0:132 offset1:134
	ds_read2_b64 v[40:43], v186 offset0:136 offset1:138
	ds_read2_b64 v[44:47], v186 offset0:140 offset1:142
	s_waitcnt lgkmcnt(3)
	v_mfma_f32_32x32x16_bf16 v[96:111], v[32:35], v[16:19], v[96:111]
	v_pk_mul_f32 v[80:81], v[80:81], v[14:15] op_sel_hi:[1,0]
	v_pk_mul_f32 v[82:83], v[82:83], v[14:15] op_sel_hi:[1,0]
	ds_read2_b64 v[32:35], v187 offset0:160 offset1:162
	s_waitcnt lgkmcnt(3)
	v_mfma_f32_32x32x16_bf16 v[96:111], v[36:39], v[20:23], v[96:111]
	v_pk_mul_f32 v[84:85], v[84:85], v[14:15] op_sel_hi:[1,0]
	v_pk_mul_f32 v[86:87], v[86:87], v[14:15] op_sel_hi:[1,0]
	ds_read2_b64 v[36:39], v187 offset0:164 offset1:166
	s_waitcnt lgkmcnt(3)
	v_mfma_f32_32x32x16_bf16 v[96:111], v[40:43], v[24:27], v[96:111]
	v_pk_mul_f32 v[88:89], v[88:89], v[14:15] op_sel_hi:[1,0]
	v_pk_mul_f32 v[90:91], v[90:91], v[14:15] op_sel_hi:[1,0]
	ds_read2_b64 v[40:43], v187 offset0:168 offset1:170
	s_waitcnt lgkmcnt(3)
	v_mfma_f32_32x32x16_bf16 v[96:111], v[44:47], v[28:31], v[96:111]
	v_pk_mul_f32 v[92:93], v[92:93], v[14:15] op_sel_hi:[1,0]
	v_pk_mul_f32 v[94:95], v[94:95], v[14:15] op_sel_hi:[1,0]
	ds_read2_b64 v[44:47], v187 offset0:172 offset1:174
	s_waitcnt lgkmcnt(3)
	v_mfma_f32_32x32x16_bf16 v[80:95], v[32:35], v[16:19], v[80:95]
	v_pk_mul_f32 v[64:65], v[64:65], v[14:15] op_sel_hi:[1,0]
	v_pk_mul_f32 v[66:67], v[66:67], v[14:15] op_sel_hi:[1,0]
	ds_read2_b64 v[32:35], v188 offset0:192 offset1:194
	s_waitcnt lgkmcnt(3)
	v_mfma_f32_32x32x16_bf16 v[80:95], v[36:39], v[20:23], v[80:95]
	v_pk_mul_f32 v[68:69], v[68:69], v[14:15] op_sel_hi:[1,0]
	v_pk_mul_f32 v[70:71], v[70:71], v[14:15] op_sel_hi:[1,0]
	ds_read2_b64 v[36:39], v188 offset0:196 offset1:198
	s_waitcnt lgkmcnt(3)
	v_mfma_f32_32x32x16_bf16 v[80:95], v[40:43], v[24:27], v[80:95]
	v_pk_mul_f32 v[72:73], v[72:73], v[14:15] op_sel_hi:[1,0]
	v_pk_mul_f32 v[74:75], v[74:75], v[14:15] op_sel_hi:[1,0]
	ds_read2_b64 v[40:43], v188 offset0:200 offset1:202
	s_waitcnt lgkmcnt(3)
	v_mfma_f32_32x32x16_bf16 v[80:95], v[44:47], v[28:31], v[80:95]
	v_pk_mul_f32 v[76:77], v[76:77], v[14:15] op_sel_hi:[1,0]
	v_pk_mul_f32 v[78:79], v[78:79], v[14:15] op_sel_hi:[1,0]
	ds_read2_b64 v[44:47], v188 offset0:204 offset1:206
	s_waitcnt lgkmcnt(3)
	v_mfma_f32_32x32x16_bf16 v[64:79], v[32:35], v[16:19], v[64:79]
	v_pk_mul_f32 v[48:49], v[48:49], v[14:15] op_sel_hi:[1,0]
	v_pk_mul_f32 v[50:51], v[50:51], v[14:15] op_sel_hi:[1,0]
	ds_read2_b64 v[32:35], v189 offset0:224 offset1:226
	s_waitcnt lgkmcnt(3)
	v_mfma_f32_32x32x16_bf16 v[64:79], v[36:39], v[20:23], v[64:79]
	v_pk_mul_f32 v[52:53], v[52:53], v[14:15] op_sel_hi:[1,0]
	v_pk_mul_f32 v[54:55], v[54:55], v[14:15] op_sel_hi:[1,0]
	ds_read2_b64 v[36:39], v189 offset0:228 offset1:230
	s_waitcnt lgkmcnt(3)
	v_mfma_f32_32x32x16_bf16 v[64:79], v[40:43], v[24:27], v[64:79]
	v_pk_mul_f32 v[56:57], v[56:57], v[14:15] op_sel_hi:[1,0]
	v_pk_mul_f32 v[58:59], v[58:59], v[14:15] op_sel_hi:[1,0]
	ds_read2_b64 v[40:43], v189 offset0:232 offset1:234
	s_waitcnt lgkmcnt(3)
	v_mfma_f32_32x32x16_bf16 v[64:79], v[44:47], v[28:31], v[64:79]
	v_pk_mul_f32 v[60:61], v[60:61], v[14:15] op_sel_hi:[1,0]
	v_pk_mul_f32 v[62:63], v[62:63], v[14:15] op_sel_hi:[1,0]
	ds_read2_b64 v[44:47], v189 offset0:236 offset1:238
	s_waitcnt lgkmcnt(3)
	v_mfma_f32_32x32x16_bf16 v[48:63], v[32:35], v[16:19], v[48:63]
	s_waitcnt lgkmcnt(2)
	v_mfma_f32_32x32x16_bf16 v[48:63], v[36:39], v[20:23], v[48:63]
	s_waitcnt lgkmcnt(1)
	v_mfma_f32_32x32x16_bf16 v[48:63], v[40:43], v[24:27], v[48:63]
	s_waitcnt lgkmcnt(0)
	v_mfma_f32_32x32x16_bf16 v[48:63], v[44:47], v[28:31], v[48:63]
.Lmla_h2_done:
	s_add_i32 s2, s24, 0x15000
	s_cmp_ge_u32 s2, 0x1f800
	s_cselect_b32 s4, 0x1f800, 0
	s_sub_i32 s2, s2, s4
	s_add_i32 s2, s2, 16
	s_add_i32 s24, s24, 0xa800
	s_cmp_eq_u32 s24, 0x1f800
	s_cselect_b32 s24, 0, s24
	v_add3_u32 v1, s2, v171, v191
	s_waitcnt vmcnt(4)
	ds_write_b128 v1, v[2:5]
	s_waitcnt vmcnt(3)
	ds_write_b128 v1, v[6:9] offset:12800
	v_add3_u32 v1, s2, v241, v242
	s_waitcnt vmcnt(2)
	ds_write_b128 v1, v[10:13] offset:256
	v_add3_u32 v1, s2, v243, v242
	v_add_u32_e32 v2, 0x6400, v1
	v_add_u32_e32 v1, 0x8600, v1
	s_waitcnt vmcnt(1)
	ds_write2_b64 v2, v[160:161], v[162:163] offset1:1
	s_waitcnt vmcnt(0)
	ds_write2_b64 v1, v[164:165], v[166:167] offset1:1
	s_add_i32 s19, s19, 64
	s_mov_b64 s[4:5], 0x2000
	v_lshl_add_u64 v[230:231], v[230:231], 0, s[92:93]
	v_lshl_add_u64 v[228:229], v[228:229], 0, s[4:5]
	v_lshl_add_u64 v[226:227], v[226:227], 0, s[38:39]
	s_add_i32 s2, s24, 16
	s_cmp_eq_u32 s3, s19
	s_cbranch_scc0 .LBB0_432
